# in-proj epilogue: pipelined lane transposition (group k stored after group k+1's transposition is issued), as in the other three GEMMs
# speedup vs baseline: 1.0018x; 1.0018x over previous
; __device__ __forceinline__ unsigned cvt_pk_bf16(float lo, float hi) { unsigned r; asm volatile("v_cvt_pk_bf16_f32 %0, %1, %2" : "=v"(r) : "v"(lo), "v"(hi)); return r; }
;     __device__ __forceinline__ void operator()(const f32x4 (&acc)[2][2][4][2], const Unit& u, int wr, int wc, int fr, int fq) const {
;     ...
;             if (rot_wave && fq < 2) {
; #pragma unroll
;                 for (int mm = 0; mm < 2; ++mm) { const float* cr = cs + (size_t)(row0 + ai * HALF + (2 * mh + mm) * 16) * 16 + 4 * fq;
;                     cc[mm][0] = *(const f32x4*)(cr); cc[mm][1] = *(const f32x4*)(cr + 8); }
;             }
; #pragma unroll
;             for (int mm = 0; mm < 2; ++mm) {
;                 const int m = 2 * mh + mm;
;                 const int row = row0 + ai * HALF + m * 16;
;                 bf16_t* rowp = O + (size_t)row * INW + col0;
; #pragma unroll
;                 for (int bj = 0; bj < 2; ++bj) {
;                     f32x4 v0 = acc[ai][bj][m][0] + bv[bj][0], v1 = acc[ai][bj][m][1] + bv[bj][1];
;                     const int cb = colt + bj * HALF;
;                     if (rot_wave && cb < 640) {
;                         const f32x4 t1 = v0, t2 = v1;
;                         v0 = t1 * cc[mm][0] - t2 * cc[mm][1]; v1 = t2 * cc[mm][0] + t1 * cc[mm][1];
;                     }
;                     if (cb < 512) { v0 = v0 * 0.125f; v1 = v1 * 0.125f; }
;                     u32x4 w; w.x = cvt_pk_bf16(v0[0], v0[1]); w.y = cvt_pk_bf16(v0[2], v0[3]); w.z = cvt_pk_bf16(v1[0], v1[1]); w.w = cvt_pk_bf16(v1[2], v1[3]);
;                     *(u32x4*)(rowp + bj * HALF) = w;
.LBB0_193:
	s_or_b64 exec, exec, s[0:1]
	s_waitcnt vmcnt(0)
	v_pk_add_f32 v[140:141], v[140:141], v[92:93]
	v_pk_add_f32 v[138:139], v[138:139], v[90:91]
	v_pk_add_f32 v[144:145], v[144:145], v[96:97]
	v_pk_add_f32 v[142:143], v[142:143], v[94:95]
	v_pk_mul_f32 v[216:217], v[138:139], v[154:155]
	v_pk_mul_f32 v[218:219], v[140:141], v[156:157]
	v_pk_mul_f32 v[212:213], v[138:139], v[158:159]
	v_pk_mul_f32 v[214:215], v[140:141], v[160:161]
	v_pk_fma_f32 v[218:219], v[144:145], v[160:161], v[218:219]
	v_pk_fma_f32 v[216:217], v[142:143], v[158:159], v[216:217]
	v_pk_fma_f32 v[214:215], v[144:145], v[156:157], v[214:215] neg_lo:[0,0,1] neg_hi:[0,0,1]
	v_pk_fma_f32 v[212:213], v[142:143], v[154:155], v[212:213] neg_lo:[0,0,1] neg_hi:[0,0,1]
	v_cndmask_b32_e64 v141, v141, v219, s[40:41]
	v_cndmask_b32_e64 v140, v140, v218, s[40:41]
	v_cndmask_b32_e64 v139, v139, v217, s[40:41]
	v_cndmask_b32_e64 v138, v138, v216, s[40:41]
	s_cmp_lt_i32 s44, 2
	v_ashrrev_i32_e32 v187, 31, v186
	v_mov_b64_e32 v[208:209], s[74:75]
	v_cndmask_b32_e64 v145, v145, v215, s[40:41]
	v_cndmask_b32_e64 v144, v144, v214, s[40:41]
	v_cndmask_b32_e64 v143, v143, v213, s[40:41]
	v_cndmask_b32_e64 v142, v142, v212, s[40:41]
	v_pk_mul_f32 v[216:217], v[140:141], s[28:29] op_sel_hi:[1,0]
	v_pk_mul_f32 v[218:219], v[138:139], s[28:29] op_sel_hi:[1,0]
	s_cselect_b64 s[42:43], -1, 0
	v_mad_i64_i32 v[210:211], s[0:1], v188, s85, v[208:209]
	v_lshlrev_b64 v[186:187], 1, v[186:187]
	v_pk_mul_f32 v[212:213], v[144:145], s[28:29] op_sel_hi:[1,0]
	v_pk_mul_f32 v[214:215], v[142:143], s[28:29] op_sel_hi:[1,0]
	v_cndmask_b32_e64 v189, v140, v216, s[42:43]
	v_cndmask_b32_e64 v141, v141, v217, s[42:43]
	v_cndmask_b32_e64 v140, v138, v218, s[42:43]
	v_lshl_add_u64 v[210:211], v[210:211], 0, v[186:187]
	v_cndmask_b32_e64 v144, v144, v212, s[42:43]
	v_cndmask_b32_e64 v145, v145, v213, s[42:43]
	v_cndmask_b32_e64 v142, v142, v214, s[42:43]
	v_cndmask_b32_e64 v143, v143, v215, s[42:43]
	v_cndmask_b32_e64 v212, v139, v219, s[42:43]
	v_cvt_pk_bf16_f32 v138, v142, v143
	v_cvt_pk_bf16_f32 v139, v144, v145
	v_cvt_pk_bf16_f32 v140, v140, v212
	v_cvt_pk_bf16_f32 v141, v189, v141
	v_pk_add_f32 v[132:133], v[132:133], v[76:77]
	v_pk_add_f32 v[130:131], v[130:131], v[74:75]
	ds_bpermute_b32 v220, v248, v138
	ds_bpermute_b32 v221, v248, v139
	ds_bpermute_b32 v222, v248, v140
	ds_bpermute_b32 v223, v248, v141
	v_lshl_add_u64 v[236:237], v[210:211], 0, v[252:253]
	v_pk_add_f32 v[136:137], v[136:137], v[80:81]
	v_pk_add_f32 v[134:135], v[134:135], v[78:79]
	v_pk_mul_f32 v[138:139], v[130:131], v[158:159]
	v_pk_mul_f32 v[140:141], v[132:133], v[160:161]
	v_pk_mul_f32 v[142:143], v[130:131], v[154:155]
	v_pk_mul_f32 v[144:145], v[132:133], v[156:157]
	v_pk_fma_f32 v[140:141], v[136:137], v[156:157], v[140:141] neg_lo:[0,0,1] neg_hi:[0,0,1]
	v_pk_fma_f32 v[138:139], v[134:135], v[154:155], v[138:139] neg_lo:[0,0,1] neg_hi:[0,0,1]
	v_pk_fma_f32 v[144:145], v[136:137], v[160:161], v[144:145]
	v_pk_fma_f32 v[142:143], v[134:135], v[158:159], v[142:143]
	v_cndmask_b32_e32 v137, v137, v141, vcc
	v_cndmask_b32_e32 v136, v136, v140, vcc
	v_cndmask_b32_e32 v135, v135, v139, vcc
	v_cndmask_b32_e32 v134, v134, v138, vcc
	v_cndmask_b32_e32 v133, v133, v145, vcc
	v_cndmask_b32_e32 v132, v132, v144, vcc
	v_cndmask_b32_e32 v131, v131, v143, vcc
	v_cndmask_b32_e32 v130, v130, v142, vcc
	s_cmpk_lt_i32 s16, 0x200
	v_pk_mul_f32 v[138:139], v[136:137], s[28:29] op_sel_hi:[1,0]
	v_pk_mul_f32 v[140:141], v[134:135], s[28:29] op_sel_hi:[1,0]
	v_pk_mul_f32 v[142:143], v[132:133], s[28:29] op_sel_hi:[1,0]
	v_pk_mul_f32 v[144:145], v[130:131], s[28:29] op_sel_hi:[1,0]
	s_cselect_b64 s[44:45], -1, 0
	v_cndmask_b32_e64 v136, v136, v138, s[44:45]
	v_cndmask_b32_e64 v137, v137, v139, s[44:45]
	v_cndmask_b32_e64 v134, v134, v140, s[44:45]
	v_cndmask_b32_e64 v135, v135, v141, s[44:45]
	v_cndmask_b32_e64 v138, v132, v142, s[44:45]
	v_cndmask_b32_e64 v133, v133, v143, s[44:45]
	v_cndmask_b32_e64 v132, v130, v144, s[44:45]
	v_cndmask_b32_e64 v139, v131, v145, s[44:45]
	v_cvt_pk_bf16_f32 v130, v134, v135
	v_cvt_pk_bf16_f32 v131, v136, v137
	v_cvt_pk_bf16_f32 v132, v132, v139
	v_cvt_pk_bf16_f32 v133, v138, v133
	ds_bpermute_b32 v224, v248, v130
	ds_bpermute_b32 v225, v248, v131
	ds_bpermute_b32 v226, v248, v132
	ds_bpermute_b32 v227, v248, v133
	v_lshl_add_u64 v[238:239], v[210:211], 0, v[252:253]
	s_waitcnt lgkmcnt(4)
	global_store_dwordx4 v[236:237], v[220:223], off
	v_pk_add_f32 v[124:125], v[124:125], v[92:93]
	v_pk_add_f32 v[122:123], v[122:123], v[90:91]
	v_mad_u64_u32 v[130:131], s[0:1], v190, s85, v[208:209]
	v_mov_b32_e32 v132, v131
	v_mad_u64_u32 v[132:133], s[0:1], v191, s85, v[132:133]
	v_pk_add_f32 v[128:129], v[128:129], v[96:97]
	v_pk_add_f32 v[126:127], v[126:127], v[94:95]
	v_pk_mul_f32 v[134:135], v[124:125], v[148:149]
	v_pk_mul_f32 v[136:137], v[122:123], v[150:151]
	v_pk_mul_f32 v[138:139], v[124:125], v[152:153]
	v_mov_b32_e32 v131, v132
	v_pk_mul_f32 v[132:133], v[122:123], v[146:147]
	v_pk_fma_f32 v[134:135], v[128:129], v[152:153], v[134:135] neg_lo:[0,0,1] neg_hi:[0,0,1]
	v_pk_fma_f32 v[138:139], v[128:129], v[148:149], v[138:139]
	v_pk_fma_f32 v[136:137], v[126:127], v[146:147], v[136:137]
	v_pk_fma_f32 v[132:133], v[126:127], v[150:151], v[132:133] neg_lo:[0,0,1] neg_hi:[0,0,1]
	v_cndmask_b32_e64 v129, v129, v135, s[40:41]
	v_cndmask_b32_e64 v128, v128, v134, s[40:41]
	v_cndmask_b32_e64 v125, v125, v139, s[40:41]
	v_cndmask_b32_e64 v124, v124, v138, s[40:41]
	v_cndmask_b32_e64 v123, v123, v137, s[40:41]
	v_cndmask_b32_e64 v122, v122, v136, s[40:41]
	v_cndmask_b32_e64 v127, v127, v133, s[40:41]
	v_cndmask_b32_e64 v126, v126, v132, s[40:41]
	v_pk_mul_f32 v[132:133], v[128:129], s[28:29] op_sel_hi:[1,0]
	v_pk_mul_f32 v[136:137], v[124:125], s[28:29] op_sel_hi:[1,0]
	v_pk_mul_f32 v[138:139], v[122:123], s[28:29] op_sel_hi:[1,0]
	v_pk_mul_f32 v[134:135], v[126:127], s[28:29] op_sel_hi:[1,0]
	v_cndmask_b32_e64 v128, v128, v132, s[42:43]
	v_cndmask_b32_e64 v132, v124, v136, s[42:43]
	v_cndmask_b32_e64 v125, v125, v137, s[42:43]
	v_cndmask_b32_e64 v124, v122, v138, s[42:43]
	v_lshl_add_u64 v[130:131], v[130:131], 0, v[186:187]
	v_cndmask_b32_e64 v129, v129, v133, s[42:43]
	v_cndmask_b32_e64 v126, v126, v134, s[42:43]
	v_cndmask_b32_e64 v127, v127, v135, s[42:43]
	v_cndmask_b32_e64 v133, v123, v139, s[42:43]
	v_cvt_pk_bf16_f32 v122, v126, v127
	v_cvt_pk_bf16_f32 v123, v128, v129
	v_cvt_pk_bf16_f32 v124, v124, v133
	v_cvt_pk_bf16_f32 v125, v132, v125
	v_pk_add_f32 v[116:117], v[116:117], v[76:77]
	v_pk_add_f32 v[114:115], v[114:115], v[74:75]
	ds_bpermute_b32 v228, v248, v122
	ds_bpermute_b32 v229, v248, v123
	ds_bpermute_b32 v230, v248, v124
	ds_bpermute_b32 v231, v248, v125
	v_lshl_add_u64 v[240:241], v[130:131], 0, v[252:253]
	s_waitcnt lgkmcnt(4)
; __device__ __forceinline__ unsigned cvt_pk_bf16(float lo, float hi) { unsigned r; asm volatile("v_cvt_pk_bf16_f32 %0, %1, %2" : "=v"(r) : "v"(lo), "v"(hi)); return r; }
;     __device__ __forceinline__ void operator()(const f32x4 (&acc)[2][2][4][2], const Unit& u, int wr, int wc, int fr, int fq) const {
;     ...
;         for (int ai = 0; ai < 2; ++ai)
; #pragma unroll
;         for (int mh = 0; mh < 2; ++mh) {
;             f32x4 cc[2][2];
; #pragma unroll
;             for (int mm = 0; mm < 2; ++mm) { cc[mm][0] = (f32x4){1.f, 1.f, 1.f, 1.f}; cc[mm][1] = (f32x4){0.f, 0.f, 0.f, 0.f}; }
;             if (rot_wave && fq < 2) {
; #pragma unroll
;                 for (int mm = 0; mm < 2; ++mm) { const float* cr = cs + (size_t)(row0 + ai * HALF + (2 * mh + mm) * 16) * 16 + 4 * fq;
;                     cc[mm][0] = *(const f32x4*)(cr); cc[mm][1] = *(const f32x4*)(cr + 8); }
;             }
; #pragma unroll
;             for (int mm = 0; mm < 2; ++mm) {
;                 const int m = 2 * mh + mm;
;                 const int row = row0 + ai * HALF + m * 16;
;                 bf16_t* rowp = O + (size_t)row * INW + col0;
; #pragma unroll
;                 for (int bj = 0; bj < 2; ++bj) {
;                     f32x4 v0 = acc[ai][bj][m][0] + bv[bj][0], v1 = acc[ai][bj][m][1] + bv[bj][1];
;                     const int cb = colt + bj * HALF;
;                     if (rot_wave && cb < 640) {
;                         const f32x4 t1 = v0, t2 = v1;
;                         v0 = t1 * cc[mm][0] - t2 * cc[mm][1]; v1 = t2 * cc[mm][0] + t1 * cc[mm][1];
;                     }
;                     if (cb < 512) { v0 = v0 * 0.125f; v1 = v1 * 0.125f; }
;                     u32x4 w; w.x = cvt_pk_bf16(v0[0], v0[1]); w.y = cvt_pk_bf16(v0[2], v0[3]); w.z = cvt_pk_bf16(v1[0], v1[1]); w.w = cvt_pk_bf16(v1[2], v1[3]);
;                     *(u32x4*)(rowp + bj * HALF) = w;
	global_store_dwordx4 v[238:239], v[224:227], off offset:256
	v_pk_add_f32 v[120:121], v[120:121], v[80:81]
	v_pk_add_f32 v[118:119], v[118:119], v[78:79]
	v_pk_mul_f32 v[124:125], v[116:117], v[148:149]
	v_pk_mul_f32 v[126:127], v[114:115], v[150:151]
	v_pk_mul_f32 v[128:129], v[116:117], v[152:153]
	v_pk_mul_f32 v[122:123], v[114:115], v[146:147]
	v_pk_fma_f32 v[124:125], v[120:121], v[152:153], v[124:125] neg_lo:[0,0,1] neg_hi:[0,0,1]
	v_pk_fma_f32 v[128:129], v[120:121], v[148:149], v[128:129]
	v_pk_fma_f32 v[126:127], v[118:119], v[146:147], v[126:127]
	v_pk_fma_f32 v[122:123], v[118:119], v[150:151], v[122:123] neg_lo:[0,0,1] neg_hi:[0,0,1]
	v_cndmask_b32_e32 v121, v121, v125, vcc
	v_cndmask_b32_e32 v120, v120, v124, vcc
	v_cndmask_b32_e32 v117, v117, v129, vcc
	v_cndmask_b32_e32 v116, v116, v128, vcc
	v_cndmask_b32_e32 v115, v115, v127, vcc
	v_cndmask_b32_e32 v114, v114, v126, vcc
	v_cndmask_b32_e32 v119, v119, v123, vcc
	v_cndmask_b32_e32 v118, v118, v122, vcc
	v_pk_mul_f32 v[122:123], v[120:121], s[28:29] op_sel_hi:[1,0]
	v_pk_mul_f32 v[126:127], v[116:117], s[28:29] op_sel_hi:[1,0]
	v_pk_mul_f32 v[128:129], v[114:115], s[28:29] op_sel_hi:[1,0]
	v_pk_mul_f32 v[124:125], v[118:119], s[28:29] op_sel_hi:[1,0]
	v_cndmask_b32_e64 v120, v120, v122, s[44:45]
	v_cndmask_b32_e64 v122, v116, v126, s[44:45]
	v_cndmask_b32_e64 v117, v117, v127, s[44:45]
	v_cndmask_b32_e64 v116, v114, v128, s[44:45]
	v_cndmask_b32_e64 v121, v121, v123, s[44:45]
	v_cndmask_b32_e64 v118, v118, v124, s[44:45]
	v_cndmask_b32_e64 v119, v119, v125, s[44:45]
	v_cndmask_b32_e64 v123, v115, v129, s[44:45]
	v_cvt_pk_bf16_f32 v114, v118, v119
	v_cvt_pk_bf16_f32 v115, v120, v121
	v_cvt_pk_bf16_f32 v116, v116, v123
	v_cvt_pk_bf16_f32 v117, v122, v117
	ds_bpermute_b32 v232, v248, v114
	ds_bpermute_b32 v233, v248, v115
	ds_bpermute_b32 v234, v248, v116
	ds_bpermute_b32 v235, v248, v117
	v_lshl_add_u64 v[242:243], v[130:131], 0, v[252:253]
	s_waitcnt lgkmcnt(4)
	global_store_dwordx4 v[240:241], v[228:231], off
	v_or_b32_e32 v130, 48, v188
	s_and_saveexec_b64 s[0:1], s[58:59]
	s_xor_b64 s[0:1], exec, s[0:1]
	v_ashrrev_i32_e32 v131, 31, v130
	s_or_saveexec_b64 s[0:1], s[0:1]
	v_or_b32_e32 v132, 32, v188
	v_ashrrev_i32_e32 v133, 31, v132
	v_mov_b32_e32 v122, 1.0
	v_mov_b32_e32 v114, 0
	v_mov_b32_e32 v115, 0
	v_mov_b32_e32 v116, 0
	v_mov_b32_e32 v117, 0
	v_mov_b32_e32 v123, 1.0
	v_mov_b32_e32 v124, 1.0
	v_mov_b32_e32 v125, 1.0
	v_mov_b32_e32 v126, 0
	v_mov_b32_e32 v127, 0
	v_mov_b32_e32 v128, 0
	v_mov_b32_e32 v129, 0
	v_mov_b32_e32 v118, 1.0
	v_mov_b32_e32 v119, 1.0
	v_mov_b32_e32 v120, 1.0
	v_mov_b32_e32 v121, 1.0
	s_xor_b64 exec, exec, s[0:1]
	s_cbranch_execz .LBB0_197
	v_lshlrev_b64 v[114:115], 6, v[132:133]
	v_lshl_add_u64 v[114:115], v[180:181], 0, v[114:115]
	v_ashrrev_i32_e32 v131, 31, v130
	global_load_dwordx4 v[122:125], v[114:115], off
	global_load_dwordx4 v[126:129], v[114:115], off offset:32
	v_lshlrev_b64 v[114:115], 6, v[130:131]
	v_lshl_add_u64 v[114:115], v[180:181], 0, v[114:115]
	global_load_dwordx4 v[118:121], v[114:115], off
	s_nop 0
	global_load_dwordx4 v[114:117], v[114:115], off offset:32
.LBB0_197:
	s_or_b64 exec, exec, s[0:1]
	v_pk_add_f32 v[108:109], v[108:109], v[92:93]
	v_pk_add_f32 v[106:107], v[106:107], v[90:91]
	v_pk_add_f32 v[112:113], v[112:113], v[96:97]
	v_pk_add_f32 v[110:111], v[110:111], v[94:95]
	s_waitcnt vmcnt(2)
	v_pk_mul_f32 v[138:139], v[108:109], v[128:129]
	v_pk_mul_f32 v[140:141], v[106:107], v[122:123]
	v_pk_mul_f32 v[142:143], v[108:109], v[124:125]
	v_pk_mul_f32 v[136:137], v[106:107], v[126:127]
	v_pk_fma_f32 v[138:139], v[112:113], v[124:125], v[138:139] neg_lo:[0,0,1] neg_hi:[0,0,1]
	v_pk_fma_f32 v[142:143], v[112:113], v[128:129], v[142:143]
	v_pk_fma_f32 v[140:141], v[110:111], v[126:127], v[140:141]
	v_pk_fma_f32 v[136:137], v[110:111], v[122:123], v[136:137] neg_lo:[0,0,1] neg_hi:[0,0,1]
	v_cndmask_b32_e64 v113, v113, v139, s[40:41]
	v_cndmask_b32_e64 v112, v112, v138, s[40:41]
	v_cndmask_b32_e64 v109, v109, v143, s[40:41]
	v_cndmask_b32_e64 v108, v108, v142, s[40:41]
	v_cndmask_b32_e64 v107, v107, v141, s[40:41]
	v_cndmask_b32_e64 v106, v106, v140, s[40:41]
	v_mov_b64_e32 v[134:135], s[74:75]
	v_cndmask_b32_e64 v111, v111, v137, s[40:41]
	v_cndmask_b32_e64 v110, v110, v136, s[40:41]
	v_pk_mul_f32 v[136:137], v[112:113], s[28:29] op_sel_hi:[1,0]
	v_pk_mul_f32 v[140:141], v[108:109], s[28:29] op_sel_hi:[1,0]
	v_pk_mul_f32 v[142:143], v[106:107], s[28:29] op_sel_hi:[1,0]
	v_mad_i64_i32 v[132:133], s[0:1], v132, s85, v[134:135]
	v_pk_mul_f32 v[138:139], v[110:111], s[28:29] op_sel_hi:[1,0]
	v_cndmask_b32_e64 v112, v112, v136, s[42:43]
	v_cndmask_b32_e64 v136, v108, v140, s[42:43]
	v_cndmask_b32_e64 v109, v109, v141, s[42:43]
	v_cndmask_b32_e64 v108, v106, v142, s[42:43]
	v_lshl_add_u64 v[132:133], v[132:133], 0, v[186:187]
	v_cndmask_b32_e64 v113, v113, v137, s[42:43]
	v_cndmask_b32_e64 v110, v110, v138, s[42:43]
	v_cndmask_b32_e64 v111, v111, v139, s[42:43]
	v_cndmask_b32_e64 v137, v107, v143, s[42:43]
	v_cvt_pk_bf16_f32 v106, v110, v111
	v_cvt_pk_bf16_f32 v107, v112, v113
	v_cvt_pk_bf16_f32 v108, v108, v137
	v_cvt_pk_bf16_f32 v109, v136, v109
	v_pk_add_f32 v[100:101], v[100:101], v[76:77]
	v_pk_add_f32 v[98:99], v[98:99], v[74:75]
	ds_bpermute_b32 v220, v248, v106
	ds_bpermute_b32 v221, v248, v107
	ds_bpermute_b32 v222, v248, v108
	ds_bpermute_b32 v223, v248, v109
	v_lshl_add_u64 v[236:237], v[132:133], 0, v[252:253]
	s_waitcnt lgkmcnt(4)
; __device__ __forceinline__ unsigned cvt_pk_bf16(float lo, float hi) { unsigned r; asm volatile("v_cvt_pk_bf16_f32 %0, %1, %2" : "=v"(r) : "v"(lo), "v"(hi)); return r; }
;     __device__ __forceinline__ void operator()(const f32x4 (&acc)[2][2][4][2], const Unit& u, int wr, int wc, int fr, int fq) const {
;     ...
;         for (int mh = 0; mh < 2; ++mh) {
;             f32x4 cc[2][2];
; #pragma unroll
;             for (int mm = 0; mm < 2; ++mm) { cc[mm][0] = (f32x4){1.f, 1.f, 1.f, 1.f}; cc[mm][1] = (f32x4){0.f, 0.f, 0.f, 0.f}; }
;             if (rot_wave && fq < 2) {
; #pragma unroll
;                 for (int mm = 0; mm < 2; ++mm) { const float* cr = cs + (size_t)(row0 + ai * HALF + (2 * mh + mm) * 16) * 16 + 4 * fq;
;                     cc[mm][0] = *(const f32x4*)(cr); cc[mm][1] = *(const f32x4*)(cr + 8); }
;             }
; #pragma unroll
;             for (int mm = 0; mm < 2; ++mm) {
;                 const int m = 2 * mh + mm;
;                 const int row = row0 + ai * HALF + m * 16;
;                 bf16_t* rowp = O + (size_t)row * INW + col0;
; #pragma unroll
;                 for (int bj = 0; bj < 2; ++bj) {
;                     f32x4 v0 = acc[ai][bj][m][0] + bv[bj][0], v1 = acc[ai][bj][m][1] + bv[bj][1];
;                     const int cb = colt + bj * HALF;
;                     if (rot_wave && cb < 640) {
;                         const f32x4 t1 = v0, t2 = v1;
;                         v0 = t1 * cc[mm][0] - t2 * cc[mm][1]; v1 = t2 * cc[mm][0] + t1 * cc[mm][1];
;                     }
;                     if (cb < 512) { v0 = v0 * 0.125f; v1 = v1 * 0.125f; }
;                     u32x4 w; w.x = cvt_pk_bf16(v0[0], v0[1]); w.y = cvt_pk_bf16(v0[2], v0[3]); w.z = cvt_pk_bf16(v1[0], v1[1]); w.w = cvt_pk_bf16(v1[2], v1[3]);
;                     *(u32x4*)(rowp + bj * HALF) = w;
;                 }
;             }
;         }
	global_store_dwordx4 v[242:243], v[232:235], off offset:256
	v_pk_add_f32 v[104:105], v[104:105], v[80:81]
	v_pk_add_f32 v[102:103], v[102:103], v[78:79]
	v_pk_mul_f32 v[106:107], v[98:99], v[126:127]
	v_pk_mul_f32 v[108:109], v[100:101], v[128:129]
	v_pk_mul_f32 v[110:111], v[98:99], v[122:123]
	v_pk_mul_f32 v[112:113], v[100:101], v[124:125]
	v_pk_fma_f32 v[108:109], v[104:105], v[124:125], v[108:109] neg_lo:[0,0,1] neg_hi:[0,0,1]
	v_pk_fma_f32 v[106:107], v[102:103], v[122:123], v[106:107] neg_lo:[0,0,1] neg_hi:[0,0,1]
	v_pk_fma_f32 v[112:113], v[104:105], v[128:129], v[112:113]
	v_pk_fma_f32 v[110:111], v[102:103], v[126:127], v[110:111]
	v_cndmask_b32_e32 v105, v105, v109, vcc
	v_cndmask_b32_e32 v104, v104, v108, vcc
	v_cndmask_b32_e32 v103, v103, v107, vcc
	v_cndmask_b32_e32 v102, v102, v106, vcc
	v_cndmask_b32_e32 v101, v101, v113, vcc
	v_cndmask_b32_e32 v100, v100, v112, vcc
	v_cndmask_b32_e32 v99, v99, v111, vcc
	v_cndmask_b32_e32 v98, v98, v110, vcc
	v_pk_mul_f32 v[106:107], v[104:105], s[28:29] op_sel_hi:[1,0]
	v_pk_mul_f32 v[108:109], v[102:103], s[28:29] op_sel_hi:[1,0]
	v_pk_mul_f32 v[110:111], v[100:101], s[28:29] op_sel_hi:[1,0]
	v_pk_mul_f32 v[112:113], v[98:99], s[28:29] op_sel_hi:[1,0]
	v_cndmask_b32_e64 v104, v104, v106, s[44:45]
	v_cndmask_b32_e64 v105, v105, v107, s[44:45]
	v_cndmask_b32_e64 v102, v102, v108, s[44:45]
	v_cndmask_b32_e64 v103, v103, v109, s[44:45]
	v_cndmask_b32_e64 v106, v100, v110, s[44:45]
	v_cndmask_b32_e64 v101, v101, v111, s[44:45]
	v_cndmask_b32_e64 v100, v98, v112, s[44:45]
	v_cndmask_b32_e64 v107, v99, v113, s[44:45]
	v_cvt_pk_bf16_f32 v98, v102, v103
	v_cvt_pk_bf16_f32 v99, v104, v105
	v_cvt_pk_bf16_f32 v100, v100, v107
	v_cvt_pk_bf16_f32 v101, v106, v101
	ds_bpermute_b32 v224, v248, v98
	ds_bpermute_b32 v225, v248, v99
	ds_bpermute_b32 v226, v248, v100
	ds_bpermute_b32 v227, v248, v101
	v_lshl_add_u64 v[238:239], v[132:133], 0, v[252:253]
	s_waitcnt lgkmcnt(4)
	global_store_dwordx4 v[236:237], v[220:223], off
	v_pk_add_f32 v[84:85], v[84:85], v[92:93]
	v_pk_add_f32 v[82:83], v[82:83], v[90:91]
	v_mad_u64_u32 v[98:99], s[0:1], v130, s85, v[134:135]
	v_mov_b32_e32 v100, v99
	v_mad_u64_u32 v[100:101], s[0:1], v131, s85, v[100:101]
	v_pk_add_f32 v[88:89], v[88:89], v[96:97]
	v_pk_add_f32 v[86:87], v[86:87], v[94:95]
	s_waitcnt vmcnt(2)
	v_pk_mul_f32 v[102:103], v[84:85], v[116:117]
	v_pk_mul_f32 v[104:105], v[82:83], v[118:119]
	v_pk_mul_f32 v[106:107], v[84:85], v[120:121]
	v_mov_b32_e32 v99, v100
	v_pk_mul_f32 v[100:101], v[82:83], v[114:115]
	v_pk_fma_f32 v[102:103], v[88:89], v[120:121], v[102:103] neg_lo:[0,0,1] neg_hi:[0,0,1]
	v_pk_fma_f32 v[106:107], v[88:89], v[116:117], v[106:107]
	v_pk_fma_f32 v[104:105], v[86:87], v[114:115], v[104:105]
	v_pk_fma_f32 v[100:101], v[86:87], v[118:119], v[100:101] neg_lo:[0,0,1] neg_hi:[0,0,1]
	v_cndmask_b32_e64 v89, v89, v103, s[40:41]
	v_cndmask_b32_e64 v88, v88, v102, s[40:41]
	v_cndmask_b32_e64 v85, v85, v107, s[40:41]
	v_cndmask_b32_e64 v84, v84, v106, s[40:41]
	v_cndmask_b32_e64 v83, v83, v105, s[40:41]
	v_cndmask_b32_e64 v82, v82, v104, s[40:41]
	v_cndmask_b32_e64 v87, v87, v101, s[40:41]
	v_cndmask_b32_e64 v86, v86, v100, s[40:41]
	v_pk_mul_f32 v[100:101], v[88:89], s[28:29] op_sel_hi:[1,0]
	v_pk_mul_f32 v[104:105], v[84:85], s[28:29] op_sel_hi:[1,0]
	v_pk_mul_f32 v[106:107], v[82:83], s[28:29] op_sel_hi:[1,0]
	v_pk_mul_f32 v[102:103], v[86:87], s[28:29] op_sel_hi:[1,0]
	v_cndmask_b32_e64 v88, v88, v100, s[42:43]
	v_cndmask_b32_e64 v100, v84, v104, s[42:43]
	v_cndmask_b32_e64 v85, v85, v105, s[42:43]
	v_cndmask_b32_e64 v84, v82, v106, s[42:43]
	v_lshl_add_u64 v[98:99], v[98:99], 0, v[186:187]
	v_cndmask_b32_e64 v89, v89, v101, s[42:43]
	v_cndmask_b32_e64 v86, v86, v102, s[42:43]
	v_cndmask_b32_e64 v87, v87, v103, s[42:43]
	v_cndmask_b32_e64 v101, v83, v107, s[42:43]
	v_cvt_pk_bf16_f32 v82, v86, v87
	v_cvt_pk_bf16_f32 v83, v88, v89
	v_cvt_pk_bf16_f32 v84, v84, v101
	v_cvt_pk_bf16_f32 v85, v100, v85
	v_pk_add_f32 v[68:69], v[68:69], v[76:77]
	v_pk_add_f32 v[66:67], v[66:67], v[74:75]
	ds_bpermute_b32 v228, v248, v82
	ds_bpermute_b32 v229, v248, v83
	ds_bpermute_b32 v230, v248, v84
	ds_bpermute_b32 v231, v248, v85
	v_lshl_add_u64 v[240:241], v[98:99], 0, v[252:253]
	s_waitcnt lgkmcnt(4)
	global_store_dwordx4 v[238:239], v[224:227], off offset:256
	v_pk_add_f32 v[72:73], v[72:73], v[80:81]
	v_pk_add_f32 v[70:71], v[70:71], v[78:79]
	v_pk_mul_f32 v[84:85], v[68:69], v[116:117]
	v_pk_mul_f32 v[86:87], v[66:67], v[118:119]
	v_pk_mul_f32 v[88:89], v[68:69], v[120:121]
	v_pk_mul_f32 v[82:83], v[66:67], v[114:115]
	v_pk_fma_f32 v[84:85], v[72:73], v[120:121], v[84:85] neg_lo:[0,0,1] neg_hi:[0,0,1]
	v_pk_fma_f32 v[88:89], v[72:73], v[116:117], v[88:89]
	v_pk_fma_f32 v[86:87], v[70:71], v[114:115], v[86:87]
	v_pk_fma_f32 v[82:83], v[70:71], v[118:119], v[82:83] neg_lo:[0,0,1] neg_hi:[0,0,1]
	v_cndmask_b32_e32 v73, v73, v85, vcc
	v_cndmask_b32_e32 v72, v72, v84, vcc
	v_cndmask_b32_e32 v69, v69, v89, vcc
	v_cndmask_b32_e32 v68, v68, v88, vcc
	v_cndmask_b32_e32 v67, v67, v87, vcc
	v_cndmask_b32_e32 v66, v66, v86, vcc
	v_cndmask_b32_e32 v71, v71, v83, vcc
	v_cndmask_b32_e32 v70, v70, v82, vcc
	v_pk_mul_f32 v[82:83], v[72:73], s[28:29] op_sel_hi:[1,0]
	v_pk_mul_f32 v[86:87], v[68:69], s[28:29] op_sel_hi:[1,0]
	v_pk_mul_f32 v[88:89], v[66:67], s[28:29] op_sel_hi:[1,0]
	v_pk_mul_f32 v[84:85], v[70:71], s[28:29] op_sel_hi:[1,0]
	v_cndmask_b32_e64 v72, v72, v82, s[44:45]
	v_cndmask_b32_e64 v82, v68, v86, s[44:45]
	v_cndmask_b32_e64 v69, v69, v87, s[44:45]
	v_cndmask_b32_e64 v68, v66, v88, s[44:45]
	v_cndmask_b32_e64 v73, v73, v83, s[44:45]
	v_cndmask_b32_e64 v70, v70, v84, s[44:45]
	v_cndmask_b32_e64 v71, v71, v85, s[44:45]
	v_cndmask_b32_e64 v83, v67, v89, s[44:45]
	v_cvt_pk_bf16_f32 v66, v70, v71
	v_cvt_pk_bf16_f32 v67, v72, v73
	v_cvt_pk_bf16_f32 v68, v68, v83
	v_cvt_pk_bf16_f32 v69, v82, v69
	ds_bpermute_b32 v232, v248, v66
	ds_bpermute_b32 v233, v248, v67
	ds_bpermute_b32 v234, v248, v68
	ds_bpermute_b32 v235, v248, v69
	v_lshl_add_u64 v[242:243], v[98:99], 0, v[252:253]
	s_waitcnt lgkmcnt(4)
	global_store_dwordx4 v[240:241], v[228:231], off
	v_add_u32_e32 v98, 0x90, v188
	s_and_saveexec_b64 s[0:1], s[58:59]
	s_xor_b64 s[0:1], exec, s[0:1]
	v_ashrrev_i32_e32 v99, 31, v98
	s_or_saveexec_b64 s[0:1], s[0:1]
	v_add_u32_e32 v100, 0x80, v188
	v_ashrrev_i32_e32 v101, 31, v100
	v_mov_b32_e32 v82, 1.0
	v_mov_b32_e32 v66, 0
	v_mov_b32_e32 v67, 0
	v_mov_b32_e32 v68, 0
	v_mov_b32_e32 v69, 0
	v_mov_b32_e32 v83, 1.0
	v_mov_b32_e32 v84, 1.0
	v_mov_b32_e32 v85, 1.0
	v_mov_b32_e32 v86, 0
	v_mov_b32_e32 v87, 0
	v_mov_b32_e32 v88, 0
	v_mov_b32_e32 v89, 0
	v_mov_b32_e32 v70, 1.0
	v_mov_b32_e32 v71, 1.0
	v_mov_b32_e32 v72, 1.0
	v_mov_b32_e32 v73, 1.0
	s_xor_b64 exec, exec, s[0:1]
	s_cbranch_execz .LBB0_201
; __device__ __forceinline__ unsigned cvt_pk_bf16(float lo, float hi) { unsigned r; asm volatile("v_cvt_pk_bf16_f32 %0, %1, %2" : "=v"(r) : "v"(lo), "v"(hi)); return r; }
;     __device__ __forceinline__ void operator()(const f32x4 (&acc)[2][2][4][2], const Unit& u, int wr, int wc, int fr, int fq) const {
;     ...
;         for (int mh = 0; mh < 2; ++mh) {
;             f32x4 cc[2][2];
; #pragma unroll
;             for (int mm = 0; mm < 2; ++mm) { cc[mm][0] = (f32x4){1.f, 1.f, 1.f, 1.f}; cc[mm][1] = (f32x4){0.f, 0.f, 0.f, 0.f}; }
;             if (rot_wave && fq < 2) {
; #pragma unroll
;                 for (int mm = 0; mm < 2; ++mm) { const float* cr = cs + (size_t)(row0 + ai * HALF + (2 * mh + mm) * 16) * 16 + 4 * fq;
;                     cc[mm][0] = *(const f32x4*)(cr); cc[mm][1] = *(const f32x4*)(cr + 8); }
;             }
; #pragma unroll
;             for (int mm = 0; mm < 2; ++mm) {
;                 const int m = 2 * mh + mm;
;                 const int row = row0 + ai * HALF + m * 16;
;                 bf16_t* rowp = O + (size_t)row * INW + col0;
; #pragma unroll
;                 for (int bj = 0; bj < 2; ++bj) {
;                     f32x4 v0 = acc[ai][bj][m][0] + bv[bj][0], v1 = acc[ai][bj][m][1] + bv[bj][1];
;                     const int cb = colt + bj * HALF;
;                     if (rot_wave && cb < 640) {
;                         const f32x4 t1 = v0, t2 = v1;
;                         v0 = t1 * cc[mm][0] - t2 * cc[mm][1]; v1 = t2 * cc[mm][0] + t1 * cc[mm][1];
;                     }
;                     if (cb < 512) { v0 = v0 * 0.125f; v1 = v1 * 0.125f; }
;                     u32x4 w; w.x = cvt_pk_bf16(v0[0], v0[1]); w.y = cvt_pk_bf16(v0[2], v0[3]); w.z = cvt_pk_bf16(v1[0], v1[1]); w.w = cvt_pk_bf16(v1[2], v1[3]);
;                     *(u32x4*)(rowp + bj * HALF) = w;
	v_lshlrev_b64 v[66:67], 6, v[100:101]
	v_lshl_add_u64 v[66:67], v[180:181], 0, v[66:67]
	v_ashrrev_i32_e32 v99, 31, v98
	global_load_dwordx4 v[82:85], v[66:67], off
	global_load_dwordx4 v[86:89], v[66:67], off offset:32
	v_lshlrev_b64 v[66:67], 6, v[98:99]
	v_lshl_add_u64 v[66:67], v[180:181], 0, v[66:67]
	global_load_dwordx4 v[70:73], v[66:67], off
	s_nop 0
	global_load_dwordx4 v[66:69], v[66:67], off offset:32
.LBB0_201:
	s_or_b64 exec, exec, s[0:1]
	v_pk_add_f32 v[60:61], v[60:61], v[92:93]
	v_pk_add_f32 v[58:59], v[58:59], v[90:91]
	v_pk_add_f32 v[64:65], v[64:65], v[96:97]
	v_pk_add_f32 v[62:63], v[62:63], v[94:95]
	s_waitcnt vmcnt(2)
	v_pk_mul_f32 v[106:107], v[60:61], v[88:89]
	v_pk_mul_f32 v[108:109], v[58:59], v[82:83]
	v_pk_mul_f32 v[110:111], v[60:61], v[84:85]
	v_pk_mul_f32 v[104:105], v[58:59], v[86:87]
	v_pk_fma_f32 v[106:107], v[64:65], v[84:85], v[106:107] neg_lo:[0,0,1] neg_hi:[0,0,1]
	v_pk_fma_f32 v[110:111], v[64:65], v[88:89], v[110:111]
	v_pk_fma_f32 v[108:109], v[62:63], v[86:87], v[108:109]
	v_pk_fma_f32 v[104:105], v[62:63], v[82:83], v[104:105] neg_lo:[0,0,1] neg_hi:[0,0,1]
	v_cndmask_b32_e64 v65, v65, v107, s[40:41]
	v_cndmask_b32_e64 v64, v64, v106, s[40:41]
	v_cndmask_b32_e64 v61, v61, v111, s[40:41]
	v_cndmask_b32_e64 v60, v60, v110, s[40:41]
	v_cndmask_b32_e64 v59, v59, v109, s[40:41]
	v_cndmask_b32_e64 v58, v58, v108, s[40:41]
	v_mov_b64_e32 v[102:103], s[74:75]
	v_cndmask_b32_e64 v63, v63, v105, s[40:41]
	v_cndmask_b32_e64 v62, v62, v104, s[40:41]
	v_pk_mul_f32 v[104:105], v[64:65], s[28:29] op_sel_hi:[1,0]
	v_pk_mul_f32 v[108:109], v[60:61], s[28:29] op_sel_hi:[1,0]
	v_pk_mul_f32 v[110:111], v[58:59], s[28:29] op_sel_hi:[1,0]
	v_mad_i64_i32 v[100:101], s[0:1], v100, s85, v[102:103]
	v_pk_mul_f32 v[106:107], v[62:63], s[28:29] op_sel_hi:[1,0]
	v_cndmask_b32_e64 v64, v64, v104, s[42:43]
	v_cndmask_b32_e64 v104, v60, v108, s[42:43]
	v_cndmask_b32_e64 v61, v61, v109, s[42:43]
	v_cndmask_b32_e64 v60, v58, v110, s[42:43]
	v_lshl_add_u64 v[100:101], v[100:101], 0, v[186:187]
	v_cndmask_b32_e64 v65, v65, v105, s[42:43]
	v_cndmask_b32_e64 v62, v62, v106, s[42:43]
	v_cndmask_b32_e64 v63, v63, v107, s[42:43]
	v_cndmask_b32_e64 v105, v59, v111, s[42:43]
	v_cvt_pk_bf16_f32 v58, v62, v63
	v_cvt_pk_bf16_f32 v59, v64, v65
	v_cvt_pk_bf16_f32 v60, v60, v105
	v_cvt_pk_bf16_f32 v61, v104, v61
	v_pk_add_f32 v[52:53], v[52:53], v[76:77]
	v_pk_add_f32 v[50:51], v[50:51], v[74:75]
	ds_bpermute_b32 v220, v248, v58
	ds_bpermute_b32 v221, v248, v59
	ds_bpermute_b32 v222, v248, v60
	ds_bpermute_b32 v223, v248, v61
	v_lshl_add_u64 v[236:237], v[100:101], 0, v[252:253]
	s_waitcnt lgkmcnt(4)
	global_store_dwordx4 v[242:243], v[232:235], off offset:256
	v_pk_add_f32 v[56:57], v[56:57], v[80:81]
	v_pk_add_f32 v[54:55], v[54:55], v[78:79]
	v_pk_mul_f32 v[58:59], v[50:51], v[86:87]
	v_pk_mul_f32 v[60:61], v[52:53], v[88:89]
	v_pk_mul_f32 v[62:63], v[50:51], v[82:83]
	v_pk_mul_f32 v[64:65], v[52:53], v[84:85]
	v_pk_fma_f32 v[60:61], v[56:57], v[84:85], v[60:61] neg_lo:[0,0,1] neg_hi:[0,0,1]
	v_pk_fma_f32 v[58:59], v[54:55], v[82:83], v[58:59] neg_lo:[0,0,1] neg_hi:[0,0,1]
	v_pk_fma_f32 v[64:65], v[56:57], v[88:89], v[64:65]
	v_pk_fma_f32 v[62:63], v[54:55], v[86:87], v[62:63]
	v_cndmask_b32_e32 v57, v57, v61, vcc
	v_cndmask_b32_e32 v56, v56, v60, vcc
	v_cndmask_b32_e32 v55, v55, v59, vcc
	v_cndmask_b32_e32 v54, v54, v58, vcc
	v_cndmask_b32_e32 v53, v53, v65, vcc
	v_cndmask_b32_e32 v52, v52, v64, vcc
	v_cndmask_b32_e32 v51, v51, v63, vcc
	v_cndmask_b32_e32 v50, v50, v62, vcc
	v_pk_mul_f32 v[58:59], v[56:57], s[28:29] op_sel_hi:[1,0]
	v_pk_mul_f32 v[60:61], v[54:55], s[28:29] op_sel_hi:[1,0]
	v_pk_mul_f32 v[62:63], v[52:53], s[28:29] op_sel_hi:[1,0]
	v_pk_mul_f32 v[64:65], v[50:51], s[28:29] op_sel_hi:[1,0]
	v_cndmask_b32_e64 v56, v56, v58, s[44:45]
	v_cndmask_b32_e64 v57, v57, v59, s[44:45]
	v_cndmask_b32_e64 v54, v54, v60, s[44:45]
	v_cndmask_b32_e64 v55, v55, v61, s[44:45]
	v_cndmask_b32_e64 v58, v52, v62, s[44:45]
	v_cndmask_b32_e64 v53, v53, v63, s[44:45]
	v_cndmask_b32_e64 v52, v50, v64, s[44:45]
	v_cndmask_b32_e64 v59, v51, v65, s[44:45]
	v_cvt_pk_bf16_f32 v50, v54, v55
	v_cvt_pk_bf16_f32 v51, v56, v57
	v_cvt_pk_bf16_f32 v52, v52, v59
	v_cvt_pk_bf16_f32 v53, v58, v53
	ds_bpermute_b32 v224, v248, v50
	ds_bpermute_b32 v225, v248, v51
	ds_bpermute_b32 v226, v248, v52
	ds_bpermute_b32 v227, v248, v53
	v_lshl_add_u64 v[238:239], v[100:101], 0, v[252:253]
	s_waitcnt lgkmcnt(4)
	global_store_dwordx4 v[236:237], v[220:223], off
	v_pk_add_f32 v[44:45], v[44:45], v[92:93]
	v_pk_add_f32 v[42:43], v[42:43], v[90:91]
	v_mad_u64_u32 v[50:51], s[0:1], v98, s85, v[102:103]
	v_mov_b32_e32 v52, v51
	v_mad_u64_u32 v[52:53], s[0:1], v99, s85, v[52:53]
	v_pk_add_f32 v[48:49], v[48:49], v[96:97]
	v_pk_add_f32 v[46:47], v[46:47], v[94:95]
	s_waitcnt vmcnt(2)
; __device__ __forceinline__ unsigned cvt_pk_bf16(float lo, float hi) { unsigned r; asm volatile("v_cvt_pk_bf16_f32 %0, %1, %2" : "=v"(r) : "v"(lo), "v"(hi)); return r; }
;     __device__ __forceinline__ void operator()(const f32x4 (&acc)[2][2][4][2], const Unit& u, int wr, int wc, int fr, int fq) const {
;     ...
;         for (int ai = 0; ai < 2; ++ai)
; #pragma unroll
;         for (int mh = 0; mh < 2; ++mh) {
;             f32x4 cc[2][2];
; #pragma unroll
;             for (int mm = 0; mm < 2; ++mm) { cc[mm][0] = (f32x4){1.f, 1.f, 1.f, 1.f}; cc[mm][1] = (f32x4){0.f, 0.f, 0.f, 0.f}; }
;             if (rot_wave && fq < 2) {
; #pragma unroll
;                 for (int mm = 0; mm < 2; ++mm) { const float* cr = cs + (size_t)(row0 + ai * HALF + (2 * mh + mm) * 16) * 16 + 4 * fq;
;                     cc[mm][0] = *(const f32x4*)(cr); cc[mm][1] = *(const f32x4*)(cr + 8); }
;             }
; #pragma unroll
;             for (int mm = 0; mm < 2; ++mm) {
;                 const int m = 2 * mh + mm;
;                 const int row = row0 + ai * HALF + m * 16;
;                 bf16_t* rowp = O + (size_t)row * INW + col0;
; #pragma unroll
;                 for (int bj = 0; bj < 2; ++bj) {
;                     f32x4 v0 = acc[ai][bj][m][0] + bv[bj][0], v1 = acc[ai][bj][m][1] + bv[bj][1];
;                     const int cb = colt + bj * HALF;
;                     if (rot_wave && cb < 640) {
;                         const f32x4 t1 = v0, t2 = v1;
;                         v0 = t1 * cc[mm][0] - t2 * cc[mm][1]; v1 = t2 * cc[mm][0] + t1 * cc[mm][1];
;                     }
;                     if (cb < 512) { v0 = v0 * 0.125f; v1 = v1 * 0.125f; }
;                     u32x4 w; w.x = cvt_pk_bf16(v0[0], v0[1]); w.y = cvt_pk_bf16(v0[2], v0[3]); w.z = cvt_pk_bf16(v1[0], v1[1]); w.w = cvt_pk_bf16(v1[2], v1[3]);
;                     *(u32x4*)(rowp + bj * HALF) = w;
	v_pk_mul_f32 v[54:55], v[44:45], v[68:69]
	v_pk_mul_f32 v[56:57], v[42:43], v[70:71]
	v_pk_mul_f32 v[58:59], v[44:45], v[72:73]
	v_mov_b32_e32 v51, v52
	v_pk_mul_f32 v[52:53], v[42:43], v[66:67]
	v_pk_fma_f32 v[54:55], v[48:49], v[72:73], v[54:55] neg_lo:[0,0,1] neg_hi:[0,0,1]
	v_pk_fma_f32 v[58:59], v[48:49], v[68:69], v[58:59]
	v_pk_fma_f32 v[56:57], v[46:47], v[66:67], v[56:57]
	v_pk_fma_f32 v[52:53], v[46:47], v[70:71], v[52:53] neg_lo:[0,0,1] neg_hi:[0,0,1]
	v_cndmask_b32_e64 v49, v49, v55, s[40:41]
	v_cndmask_b32_e64 v48, v48, v54, s[40:41]
	v_cndmask_b32_e64 v45, v45, v59, s[40:41]
	v_cndmask_b32_e64 v44, v44, v58, s[40:41]
	v_cndmask_b32_e64 v43, v43, v57, s[40:41]
	v_cndmask_b32_e64 v42, v42, v56, s[40:41]
	v_cndmask_b32_e64 v47, v47, v53, s[40:41]
	v_cndmask_b32_e64 v46, v46, v52, s[40:41]
	v_pk_mul_f32 v[52:53], v[48:49], s[28:29] op_sel_hi:[1,0]
	v_pk_mul_f32 v[56:57], v[44:45], s[28:29] op_sel_hi:[1,0]
	v_pk_mul_f32 v[58:59], v[42:43], s[28:29] op_sel_hi:[1,0]
	v_pk_mul_f32 v[54:55], v[46:47], s[28:29] op_sel_hi:[1,0]
	v_cndmask_b32_e64 v48, v48, v52, s[42:43]
	v_cndmask_b32_e64 v52, v44, v56, s[42:43]
	v_cndmask_b32_e64 v45, v45, v57, s[42:43]
	v_cndmask_b32_e64 v44, v42, v58, s[42:43]
	v_lshl_add_u64 v[50:51], v[50:51], 0, v[186:187]
	v_cndmask_b32_e64 v49, v49, v53, s[42:43]
	v_cndmask_b32_e64 v46, v46, v54, s[42:43]
	v_cndmask_b32_e64 v47, v47, v55, s[42:43]
	v_cndmask_b32_e64 v53, v43, v59, s[42:43]
	v_cvt_pk_bf16_f32 v42, v46, v47
	v_cvt_pk_bf16_f32 v43, v48, v49
	v_cvt_pk_bf16_f32 v44, v44, v53
	v_cvt_pk_bf16_f32 v45, v52, v45
	v_pk_add_f32 v[36:37], v[36:37], v[76:77]
	v_pk_add_f32 v[34:35], v[34:35], v[74:75]
	ds_bpermute_b32 v228, v248, v42
	ds_bpermute_b32 v229, v248, v43
	ds_bpermute_b32 v230, v248, v44
	ds_bpermute_b32 v231, v248, v45
	v_lshl_add_u64 v[240:241], v[50:51], 0, v[252:253]
	s_waitcnt lgkmcnt(4)
	global_store_dwordx4 v[238:239], v[224:227], off offset:256
	v_pk_add_f32 v[40:41], v[40:41], v[80:81]
	v_pk_add_f32 v[38:39], v[38:39], v[78:79]
	v_pk_mul_f32 v[44:45], v[36:37], v[68:69]
	v_pk_mul_f32 v[46:47], v[34:35], v[70:71]
	v_pk_mul_f32 v[48:49], v[36:37], v[72:73]
	v_pk_mul_f32 v[42:43], v[34:35], v[66:67]
	v_pk_fma_f32 v[44:45], v[40:41], v[72:73], v[44:45] neg_lo:[0,0,1] neg_hi:[0,0,1]
	v_pk_fma_f32 v[48:49], v[40:41], v[68:69], v[48:49]
	v_pk_fma_f32 v[46:47], v[38:39], v[66:67], v[46:47]
	v_pk_fma_f32 v[42:43], v[38:39], v[70:71], v[42:43] neg_lo:[0,0,1] neg_hi:[0,0,1]
	v_cndmask_b32_e32 v41, v41, v45, vcc
	v_cndmask_b32_e32 v40, v40, v44, vcc
	v_cndmask_b32_e32 v37, v37, v49, vcc
	v_cndmask_b32_e32 v36, v36, v48, vcc
	v_cndmask_b32_e32 v35, v35, v47, vcc
	v_cndmask_b32_e32 v34, v34, v46, vcc
	v_cndmask_b32_e32 v39, v39, v43, vcc
	v_cndmask_b32_e32 v38, v38, v42, vcc
	v_pk_mul_f32 v[42:43], v[40:41], s[28:29] op_sel_hi:[1,0]
	v_pk_mul_f32 v[46:47], v[36:37], s[28:29] op_sel_hi:[1,0]
	v_pk_mul_f32 v[48:49], v[34:35], s[28:29] op_sel_hi:[1,0]
	v_pk_mul_f32 v[44:45], v[38:39], s[28:29] op_sel_hi:[1,0]
	v_cndmask_b32_e64 v40, v40, v42, s[44:45]
	v_cndmask_b32_e64 v42, v36, v46, s[44:45]
	v_cndmask_b32_e64 v37, v37, v47, s[44:45]
	v_cndmask_b32_e64 v36, v34, v48, s[44:45]
	v_cndmask_b32_e64 v41, v41, v43, s[44:45]
	v_cndmask_b32_e64 v38, v38, v44, s[44:45]
	v_cndmask_b32_e64 v39, v39, v45, s[44:45]
	v_cndmask_b32_e64 v43, v35, v49, s[44:45]
	v_cvt_pk_bf16_f32 v34, v38, v39
	v_cvt_pk_bf16_f32 v35, v40, v41
	v_cvt_pk_bf16_f32 v36, v36, v43
	v_cvt_pk_bf16_f32 v37, v42, v37
	ds_bpermute_b32 v232, v248, v34
	ds_bpermute_b32 v233, v248, v35
	ds_bpermute_b32 v234, v248, v36
	ds_bpermute_b32 v235, v248, v37
	v_lshl_add_u64 v[242:243], v[50:51], 0, v[252:253]
	s_waitcnt lgkmcnt(4)
	global_store_dwordx4 v[240:241], v[228:231], off
	v_add_u32_e32 v50, 0xb0, v188
	s_and_saveexec_b64 s[0:1], s[58:59]
	s_xor_b64 s[0:1], exec, s[0:1]
	v_ashrrev_i32_e32 v51, 31, v50
	s_or_saveexec_b64 s[0:1], s[0:1]
	v_add_u32_e32 v52, 0xa0, v188
	v_ashrrev_i32_e32 v53, 31, v52
	v_mov_b32_e32 v42, 1.0
	v_mov_b32_e32 v34, 0
	v_mov_b32_e32 v35, 0
	v_mov_b32_e32 v36, 0
	v_mov_b32_e32 v37, 0
	v_mov_b32_e32 v43, 1.0
	v_mov_b32_e32 v44, 1.0
	v_mov_b32_e32 v45, 1.0
	v_mov_b32_e32 v46, 0
	v_mov_b32_e32 v47, 0
	v_mov_b32_e32 v48, 0
	v_mov_b32_e32 v49, 0
	v_mov_b32_e32 v38, 1.0
	v_mov_b32_e32 v39, 1.0
	v_mov_b32_e32 v40, 1.0
	v_mov_b32_e32 v41, 1.0
	s_xor_b64 exec, exec, s[0:1]
	s_cbranch_execz .LBB0_205
	v_lshlrev_b64 v[34:35], 6, v[52:53]
	v_lshl_add_u64 v[34:35], v[180:181], 0, v[34:35]
	v_ashrrev_i32_e32 v51, 31, v50
	global_load_dwordx4 v[42:45], v[34:35], off
	global_load_dwordx4 v[46:49], v[34:35], off offset:32
	v_lshlrev_b64 v[34:35], 6, v[50:51]
	v_lshl_add_u64 v[34:35], v[180:181], 0, v[34:35]
	global_load_dwordx4 v[38:41], v[34:35], off
	s_nop 0
	global_load_dwordx4 v[34:37], v[34:35], off offset:32
; __device__ __forceinline__ unsigned cvt_pk_bf16(float lo, float hi) { unsigned r; asm volatile("v_cvt_pk_bf16_f32 %0, %1, %2" : "=v"(r) : "v"(lo), "v"(hi)); return r; }
;     __device__ __forceinline__ void operator()(const f32x4 (&acc)[2][2][4][2], const Unit& u, int wr, int wc, int fr, int fq) const {
;     ...
;             if (rot_wave && fq < 2) {
; #pragma unroll
;                 for (int mm = 0; mm < 2; ++mm) { const float* cr = cs + (size_t)(row0 + ai * HALF + (2 * mh + mm) * 16) * 16 + 4 * fq;
;                     cc[mm][0] = *(const f32x4*)(cr); cc[mm][1] = *(const f32x4*)(cr + 8); }
;             }
; #pragma unroll
;             for (int mm = 0; mm < 2; ++mm) {
;                 const int m = 2 * mh + mm;
;                 const int row = row0 + ai * HALF + m * 16;
;                 bf16_t* rowp = O + (size_t)row * INW + col0;
; #pragma unroll
;                 for (int bj = 0; bj < 2; ++bj) {
;                     f32x4 v0 = acc[ai][bj][m][0] + bv[bj][0], v1 = acc[ai][bj][m][1] + bv[bj][1];
;                     const int cb = colt + bj * HALF;
;                     if (rot_wave && cb < 640) {
;                         const f32x4 t1 = v0, t2 = v1;
;                         v0 = t1 * cc[mm][0] - t2 * cc[mm][1]; v1 = t2 * cc[mm][0] + t1 * cc[mm][1];
;                     }
;                     if (cb < 512) { v0 = v0 * 0.125f; v1 = v1 * 0.125f; }
;                     u32x4 w; w.x = cvt_pk_bf16(v0[0], v0[1]); w.y = cvt_pk_bf16(v0[2], v0[3]); w.z = cvt_pk_bf16(v1[0], v1[1]); w.w = cvt_pk_bf16(v1[2], v1[3]);
;                     *(u32x4*)(rowp + bj * HALF) = w;
.LBB0_205:
	s_or_b64 exec, exec, s[0:1]
	v_pk_add_f32 v[28:29], v[28:29], v[92:93]
	v_pk_add_f32 v[26:27], v[26:27], v[90:91]
	v_pk_add_f32 v[32:33], v[32:33], v[96:97]
	v_pk_add_f32 v[30:31], v[30:31], v[94:95]
	s_waitcnt vmcnt(2)
	v_pk_mul_f32 v[58:59], v[28:29], v[48:49]
	v_pk_mul_f32 v[60:61], v[26:27], v[42:43]
	v_pk_mul_f32 v[62:63], v[28:29], v[44:45]
	v_pk_mul_f32 v[56:57], v[26:27], v[46:47]
	v_pk_fma_f32 v[58:59], v[32:33], v[44:45], v[58:59] neg_lo:[0,0,1] neg_hi:[0,0,1]
	v_pk_fma_f32 v[62:63], v[32:33], v[48:49], v[62:63]
	v_pk_fma_f32 v[60:61], v[30:31], v[46:47], v[60:61]
	v_pk_fma_f32 v[56:57], v[30:31], v[42:43], v[56:57] neg_lo:[0,0,1] neg_hi:[0,0,1]
	v_cndmask_b32_e64 v33, v33, v59, s[40:41]
	v_cndmask_b32_e64 v32, v32, v58, s[40:41]
	v_cndmask_b32_e64 v29, v29, v63, s[40:41]
	v_cndmask_b32_e64 v28, v28, v62, s[40:41]
	v_cndmask_b32_e64 v27, v27, v61, s[40:41]
	v_cndmask_b32_e64 v26, v26, v60, s[40:41]
	v_mov_b64_e32 v[54:55], s[74:75]
	v_cndmask_b32_e64 v31, v31, v57, s[40:41]
	v_cndmask_b32_e64 v30, v30, v56, s[40:41]
	v_pk_mul_f32 v[56:57], v[32:33], s[28:29] op_sel_hi:[1,0]
	v_pk_mul_f32 v[60:61], v[28:29], s[28:29] op_sel_hi:[1,0]
	v_pk_mul_f32 v[62:63], v[26:27], s[28:29] op_sel_hi:[1,0]
	v_mad_i64_i32 v[52:53], s[0:1], v52, s85, v[54:55]
	v_pk_mul_f32 v[58:59], v[30:31], s[28:29] op_sel_hi:[1,0]
	v_cndmask_b32_e64 v32, v32, v56, s[42:43]
	v_cndmask_b32_e64 v56, v28, v60, s[42:43]
	v_cndmask_b32_e64 v29, v29, v61, s[42:43]
	v_cndmask_b32_e64 v28, v26, v62, s[42:43]
	v_lshl_add_u64 v[52:53], v[52:53], 0, v[186:187]
	v_cndmask_b32_e64 v33, v33, v57, s[42:43]
	v_cndmask_b32_e64 v30, v30, v58, s[42:43]
	v_cndmask_b32_e64 v31, v31, v59, s[42:43]
	v_cndmask_b32_e64 v57, v27, v63, s[42:43]
	v_cvt_pk_bf16_f32 v26, v30, v31
	v_cvt_pk_bf16_f32 v27, v32, v33
	v_cvt_pk_bf16_f32 v28, v28, v57
	v_cvt_pk_bf16_f32 v29, v56, v29
	v_pk_add_f32 v[20:21], v[20:21], v[76:77]
	v_pk_add_f32 v[18:19], v[18:19], v[74:75]
	ds_bpermute_b32 v220, v248, v26
	ds_bpermute_b32 v221, v248, v27
	ds_bpermute_b32 v222, v248, v28
	ds_bpermute_b32 v223, v248, v29
	v_lshl_add_u64 v[236:237], v[52:53], 0, v[252:253]
	s_waitcnt lgkmcnt(4)
	global_store_dwordx4 v[242:243], v[232:235], off offset:256
	v_pk_add_f32 v[24:25], v[24:25], v[80:81]
	v_pk_add_f32 v[22:23], v[22:23], v[78:79]
	v_pk_mul_f32 v[26:27], v[18:19], v[46:47]
	v_pk_mul_f32 v[28:29], v[20:21], v[48:49]
	v_pk_mul_f32 v[30:31], v[18:19], v[42:43]
	v_pk_mul_f32 v[32:33], v[20:21], v[44:45]
	v_pk_fma_f32 v[28:29], v[24:25], v[44:45], v[28:29] neg_lo:[0,0,1] neg_hi:[0,0,1]
	v_pk_fma_f32 v[26:27], v[22:23], v[42:43], v[26:27] neg_lo:[0,0,1] neg_hi:[0,0,1]
	v_pk_fma_f32 v[32:33], v[24:25], v[48:49], v[32:33]
	v_pk_fma_f32 v[30:31], v[22:23], v[46:47], v[30:31]
	v_cndmask_b32_e32 v25, v25, v29, vcc
	v_cndmask_b32_e32 v24, v24, v28, vcc
	v_cndmask_b32_e32 v23, v23, v27, vcc
	v_cndmask_b32_e32 v22, v22, v26, vcc
	v_cndmask_b32_e32 v21, v21, v33, vcc
	v_cndmask_b32_e32 v20, v20, v32, vcc
	v_cndmask_b32_e32 v19, v19, v31, vcc
	v_cndmask_b32_e32 v18, v18, v30, vcc
	v_pk_mul_f32 v[26:27], v[24:25], s[28:29] op_sel_hi:[1,0]
	v_pk_mul_f32 v[28:29], v[22:23], s[28:29] op_sel_hi:[1,0]
	v_pk_mul_f32 v[30:31], v[20:21], s[28:29] op_sel_hi:[1,0]
	v_pk_mul_f32 v[32:33], v[18:19], s[28:29] op_sel_hi:[1,0]
	v_cndmask_b32_e64 v24, v24, v26, s[44:45]
	v_cndmask_b32_e64 v25, v25, v27, s[44:45]
	v_cndmask_b32_e64 v22, v22, v28, s[44:45]
	v_cndmask_b32_e64 v23, v23, v29, s[44:45]
	v_cndmask_b32_e64 v26, v20, v30, s[44:45]
	v_cndmask_b32_e64 v21, v21, v31, s[44:45]
	v_cndmask_b32_e64 v20, v18, v32, s[44:45]
	v_cndmask_b32_e64 v27, v19, v33, s[44:45]
	v_cvt_pk_bf16_f32 v18, v22, v23
	v_cvt_pk_bf16_f32 v19, v24, v25
	v_cvt_pk_bf16_f32 v20, v20, v27
	v_cvt_pk_bf16_f32 v21, v26, v21
	ds_bpermute_b32 v224, v248, v18
	ds_bpermute_b32 v225, v248, v19
	ds_bpermute_b32 v226, v248, v20
	ds_bpermute_b32 v227, v248, v21
	v_lshl_add_u64 v[238:239], v[52:53], 0, v[252:253]
	s_waitcnt lgkmcnt(4)
; __device__ __forceinline__ unsigned cvt_pk_bf16(float lo, float hi) { unsigned r; asm volatile("v_cvt_pk_bf16_f32 %0, %1, %2" : "=v"(r) : "v"(lo), "v"(hi)); return r; }
;     ...
;         if constexpr (!Epi::AFTER_DRAIN) { E(acc, cur, wr, wc, fr, fq); S.done(cur); }
;         if (!has_next) break;
;     __device__ __forceinline__ void operator()(const f32x4 (&acc)[2][2][4][2], const Unit& u, int wr, int wc, int fr, int fq) const {
;     ...
;             for (int mm = 0; mm < 2; ++mm) {
;                 const int m = 2 * mh + mm;
;                 const int row = row0 + ai * HALF + m * 16;
;                 bf16_t* rowp = O + (size_t)row * INW + col0;
; #pragma unroll
;                 for (int bj = 0; bj < 2; ++bj) {
;                     f32x4 v0 = acc[ai][bj][m][0] + bv[bj][0], v1 = acc[ai][bj][m][1] + bv[bj][1];
;                     const int cb = colt + bj * HALF;
;                     if (rot_wave && cb < 640) {
;                         const f32x4 t1 = v0, t2 = v1;
;                         v0 = t1 * cc[mm][0] - t2 * cc[mm][1]; v1 = t2 * cc[mm][0] + t1 * cc[mm][1];
;                     }
;                     if (cb < 512) { v0 = v0 * 0.125f; v1 = v1 * 0.125f; }
;                     u32x4 w; w.x = cvt_pk_bf16(v0[0], v0[1]); w.y = cvt_pk_bf16(v0[2], v0[3]); w.z = cvt_pk_bf16(v1[0], v1[1]); w.w = cvt_pk_bf16(v1[2], v1[3]);
;                     *(u32x4*)(rowp + bj * HALF) = w;
;                 }
;             }
;         }
;     }
	global_store_dwordx4 v[236:237], v[220:223], off
	v_pk_add_f32 v[12:13], v[12:13], v[92:93]
	v_pk_add_f32 v[10:11], v[10:11], v[90:91]
	v_mad_u64_u32 v[18:19], s[0:1], v50, s85, v[54:55]
	v_mov_b32_e32 v20, v19
	v_mad_u64_u32 v[20:21], s[0:1], v51, s85, v[20:21]
	v_pk_add_f32 v[16:17], v[16:17], v[96:97]
	v_pk_add_f32 v[14:15], v[14:15], v[94:95]
	s_waitcnt vmcnt(2)
	v_pk_mul_f32 v[22:23], v[12:13], v[36:37]
	v_pk_mul_f32 v[24:25], v[10:11], v[38:39]
	v_pk_mul_f32 v[26:27], v[12:13], v[40:41]
	v_mov_b32_e32 v19, v20
	v_pk_mul_f32 v[20:21], v[10:11], v[34:35]
	v_pk_fma_f32 v[22:23], v[16:17], v[40:41], v[22:23] neg_lo:[0,0,1] neg_hi:[0,0,1]
	v_pk_fma_f32 v[26:27], v[16:17], v[36:37], v[26:27]
	v_pk_fma_f32 v[24:25], v[14:15], v[34:35], v[24:25]
	v_pk_fma_f32 v[20:21], v[14:15], v[38:39], v[20:21] neg_lo:[0,0,1] neg_hi:[0,0,1]
	v_cndmask_b32_e64 v17, v17, v23, s[40:41]
	v_cndmask_b32_e64 v16, v16, v22, s[40:41]
	v_cndmask_b32_e64 v13, v13, v27, s[40:41]
	v_cndmask_b32_e64 v12, v12, v26, s[40:41]
	v_cndmask_b32_e64 v11, v11, v25, s[40:41]
	v_cndmask_b32_e64 v10, v10, v24, s[40:41]
	v_cndmask_b32_e64 v15, v15, v21, s[40:41]
	v_cndmask_b32_e64 v14, v14, v20, s[40:41]
	v_pk_mul_f32 v[20:21], v[16:17], s[28:29] op_sel_hi:[1,0]
	v_pk_mul_f32 v[24:25], v[12:13], s[28:29] op_sel_hi:[1,0]
	v_pk_mul_f32 v[26:27], v[10:11], s[28:29] op_sel_hi:[1,0]
	v_pk_mul_f32 v[22:23], v[14:15], s[28:29] op_sel_hi:[1,0]
	v_cndmask_b32_e64 v16, v16, v20, s[42:43]
	v_cndmask_b32_e64 v20, v12, v24, s[42:43]
	v_cndmask_b32_e64 v13, v13, v25, s[42:43]
	v_cndmask_b32_e64 v12, v10, v26, s[42:43]
	v_lshl_add_u64 v[18:19], v[18:19], 0, v[186:187]
	v_cndmask_b32_e64 v17, v17, v21, s[42:43]
	v_cndmask_b32_e64 v14, v14, v22, s[42:43]
	v_cndmask_b32_e64 v15, v15, v23, s[42:43]
	v_cndmask_b32_e64 v21, v11, v27, s[42:43]
	v_cvt_pk_bf16_f32 v10, v14, v15
	v_cvt_pk_bf16_f32 v11, v16, v17
	v_cvt_pk_bf16_f32 v12, v12, v21
	v_cvt_pk_bf16_f32 v13, v20, v13
	v_pk_add_f32 v[4:5], v[4:5], v[76:77]
	v_pk_add_f32 v[2:3], v[2:3], v[74:75]
	ds_bpermute_b32 v228, v248, v10
	ds_bpermute_b32 v229, v248, v11
	ds_bpermute_b32 v230, v248, v12
	ds_bpermute_b32 v231, v248, v13
	v_lshl_add_u64 v[240:241], v[18:19], 0, v[252:253]
	s_waitcnt lgkmcnt(4)
	global_store_dwordx4 v[238:239], v[224:227], off offset:256
	v_pk_add_f32 v[8:9], v[8:9], v[80:81]
	v_pk_add_f32 v[6:7], v[6:7], v[78:79]
	v_pk_mul_f32 v[12:13], v[4:5], v[36:37]
	v_pk_mul_f32 v[14:15], v[2:3], v[38:39]
	v_pk_mul_f32 v[16:17], v[4:5], v[40:41]
	v_pk_mul_f32 v[10:11], v[2:3], v[34:35]
	v_pk_fma_f32 v[12:13], v[8:9], v[40:41], v[12:13] neg_lo:[0,0,1] neg_hi:[0,0,1]
	v_pk_fma_f32 v[16:17], v[8:9], v[36:37], v[16:17]
	v_pk_fma_f32 v[14:15], v[6:7], v[34:35], v[14:15]
	v_pk_fma_f32 v[10:11], v[6:7], v[38:39], v[10:11] neg_lo:[0,0,1] neg_hi:[0,0,1]
	v_cndmask_b32_e32 v9, v9, v13, vcc
	v_cndmask_b32_e32 v8, v8, v12, vcc
	v_cndmask_b32_e32 v5, v5, v17, vcc
	v_cndmask_b32_e32 v4, v4, v16, vcc
	v_cndmask_b32_e32 v3, v3, v15, vcc
	v_cndmask_b32_e32 v2, v2, v14, vcc
	v_cndmask_b32_e32 v7, v7, v11, vcc
	v_cndmask_b32_e32 v6, v6, v10, vcc
	v_pk_mul_f32 v[10:11], v[8:9], s[28:29] op_sel_hi:[1,0]
	v_pk_mul_f32 v[14:15], v[4:5], s[28:29] op_sel_hi:[1,0]
	v_pk_mul_f32 v[16:17], v[2:3], s[28:29] op_sel_hi:[1,0]
	v_pk_mul_f32 v[12:13], v[6:7], s[28:29] op_sel_hi:[1,0]
	v_cndmask_b32_e64 v8, v8, v10, s[44:45]
	v_cndmask_b32_e64 v10, v4, v14, s[44:45]
	v_cndmask_b32_e64 v5, v5, v15, s[44:45]
	v_cndmask_b32_e64 v4, v2, v16, s[44:45]
	s_andn2_b64 vcc, exec, s[38:39]
	s_mov_b64 s[0:1], -1
	v_cndmask_b32_e64 v9, v9, v11, s[44:45]
	v_cndmask_b32_e64 v6, v6, v12, s[44:45]
	v_cndmask_b32_e64 v7, v7, v13, s[44:45]
	v_cndmask_b32_e64 v11, v3, v17, s[44:45]
	v_cvt_pk_bf16_f32 v2, v6, v7
	v_cvt_pk_bf16_f32 v3, v8, v9
	v_cvt_pk_bf16_f32 v4, v4, v11
	v_cvt_pk_bf16_f32 v5, v10, v5
	ds_bpermute_b32 v232, v248, v2
	ds_bpermute_b32 v233, v248, v3
	ds_bpermute_b32 v234, v248, v4
	ds_bpermute_b32 v235, v248, v5
	v_lshl_add_u64 v[242:243], v[18:19], 0, v[252:253]
	s_waitcnt lgkmcnt(4)
	global_store_dwordx4 v[240:241], v[228:231], off
	s_waitcnt lgkmcnt(0)
	global_store_dwordx4 v[242:243], v[232:235], off offset:256
	s_cbranch_vccnz .LBB0_182
	s_andn2_b64 vcc, exec, s[20:21]
	s_cbranch_vccnz .LBB0_181
	s_barrier
	s_branch .LBB0_181
